# NA loop: bias, mask, exp, row-sum and pack section specialised per query block, structurally masked score registers dropped
# speedup vs baseline: 1.0082x; 1.0082x over previous
; DI f32x16 mfma32(bf16x8 a, bf16x8 b, f32x16 c) { return __builtin_amdgcn_mfma_f32_32x32x16_bf16(a, b, c, 0, 0, 0); }
; DI bool softmax_tile(f32x16& s0, f32x16& s1, float& m, float& l, float& alpha, bf16x8* pf, int lane, bool first, bool check) {
;     ...
;   float sum = 0.f;
; #pragma unroll
;   for (int i = 0; i < 16; ++i) { s0[i] = __builtin_amdgcn_exp2f(s0[i]); sum += s0[i]; }
; #pragma unroll
;   for (int i = 0; i < 16; ++i) { s1[i] = __builtin_amdgcn_exp2f(s1[i]); sum += s1[i]; }
;   l += sum;
;   pf[0] = pack8(s0, 0); pf[1] = pack8(s0, 8); pf[2] = pack8(s1, 0); pf[3] = pack8(s1, 8);
; DI void attn_na_unit(const Params& p, int li, int b, int r, int hp, char* smem) {
;     ...
;     {
;       bf16x8 kf[8];
; #pragma unroll
;       for (int s = 0; s < 4; ++s) {
;         kf[2 * s] = *(const bf16x8*)(ks + r32 * KR + (hs * 64 + s * 16 + hh * 8) * 2);
;         kf[2 * s + 1] = *(const bf16x8*)(ks + (32 + r32) * KR + (hs * 64 + s * 16 + hh * 8) * 2);
;       }
;       __builtin_amdgcn_sched_barrier(0); __builtin_amdgcn_s_setprio(1);
; #pragma unroll
;       for (int s = 0; s < 4; ++s) { s0 = mfma32(kf[2 * s], qf[s], s0); s1 = mfma32(kf[2 * s + 1], qf[s], s1); }
;     __builtin_amdgcn_s_setprio(0);
; }
;     const int drow = rs + kt - r + 7;
;     const float* trow = tab + hs * 465 + drow * 31;
; #pragma unroll
;     for (int i = 0; i < 16; ++i) {
;       const int kc0 = (i & 3) + 8 * (i >> 2) + 4 * hh;
;       const int kc1 = kc0 + 32;
;       const bool v0 = (unsigned)(kc0 - cs) < 16u;
;       const bool v1 = (unsigned)(kc1 - cs) < 16u;
;       const int d0 = v0 ? (kc0 - wq + 15) : 0;
;       const int d1 = v1 ? (kc1 - wq + 15) : 0;
;       const float b0 = trow[d0], b1 = trow[d1];
;       s0[i] = v0 ? s0[i] + b0 : -1e30f;
;       s1[i] = v1 ? s1[i] + b1 : -1e30f;
;     }
.LBB0_1541:
	ds_read_b128 v[150:153], v123
	ds_read_b128 v[154:157], v123 offset:32
	ds_read_b128 v[158:161], v123 offset:8704
	ds_read_b128 v[162:165], v123 offset:8736
	ds_read_b128 v[166:169], v123 offset:64
	ds_read_b128 v[170:173], v123 offset:96
	ds_read_b128 v[174:177], v123 offset:8768
	ds_read_b128 v[178:181], v123 offset:8800
	v_xor_b32_e32 v32, 0x80000000, v128
	v_mov_b32_e32 v33, v32
	v_mov_b64_e32 v[34:35], v[32:33]
	v_mov_b64_e32 v[36:37], v[32:33]
	v_mov_b64_e32 v[38:39], v[32:33]
	v_mov_b64_e32 v[40:41], v[32:33]
	v_mov_b64_e32 v[42:43], v[32:33]
	v_mov_b64_e32 v[44:45], v[32:33]
	v_mov_b64_e32 v[46:47], v[32:33]
	s_setprio 1
	s_waitcnt lgkmcnt(7)
	v_mfma_f32_32x32x16_bf16 v[48:63], v[150:153], v[64:67], v[32:47]
	s_waitcnt lgkmcnt(5)
	v_mfma_f32_32x32x16_bf16 v[32:47], v[158:161], v[64:67], v[32:47]
	v_mfma_f32_32x32x16_bf16 v[48:63], v[154:157], v[68:71], v[48:63]
	s_waitcnt lgkmcnt(4)
	v_mfma_f32_32x32x16_bf16 v[32:47], v[162:165], v[68:71], v[32:47]
	s_waitcnt lgkmcnt(3)
	v_mfma_f32_32x32x16_bf16 v[48:63], v[166:169], v[72:75], v[48:63]
	s_waitcnt lgkmcnt(1)
	v_mfma_f32_32x32x16_bf16 v[32:47], v[174:177], v[72:75], v[32:47]
	v_mfma_f32_32x32x16_bf16 v[48:63], v[170:173], v[76:79], v[48:63]
	s_waitcnt lgkmcnt(0)
	v_mfma_f32_32x32x16_bf16 v[32:47], v[178:181], v[76:79], v[32:47]
	s_setprio 0
	s_bitcmp1_b32 s100, 6
	s_cbranch_scc1 .Lna_el_q1
	v_add_u32_e32 v149, s9, v130
	ds_read_b32 v150, v149 offset:868
	ds_read_b32 v151, v149 offset:872
	ds_read_b32 v152, v149 offset:876
	ds_read_b32 v153, v149 offset:880
	ds_read_b32 v154, v149 offset:900
	ds_read_b32 v155, v149 offset:904
	ds_read_b32 v156, v149 offset:908
	ds_read_b32 v157, v149 offset:912
	ds_read_b32 v158, v149 offset:932
	ds_read_b32 v159, v149 offset:936
	ds_read_b32 v160, v149 offset:940
	ds_read_b32 v161, v149 offset:944
	ds_read_b32 v162, v149 offset:964
	ds_read_b32 v163, v149 offset:968
	ds_read_b32 v164, v149 offset:972
	ds_read_b32 v165, v149 offset:976
	v_add_u32_e32 v149, s9, v129
	ds_read_b32 v166, v149 offset:868
	v_add_u32_e32 v149, s9, v131
	ds_read_b32 v167, v149 offset:868
	v_add_u32_e32 v149, s9, v132
	ds_read_b32 v168, v149 offset:868
	v_add_u32_e32 v149, s9, v133
	ds_read_b32 v169, v149 offset:868
	s_waitcnt lgkmcnt(0)
	s_nop 7
	v_add_f32_e32 v48, v48, v150
	v_cndmask_b32_e64 v48, v195, v48, s[76:77]
	v_exp_f32_e32 v48, v48
	v_add_f32_e32 v49, v49, v151
	v_cndmask_b32_e64 v49, v195, v49, s[90:91]
	v_exp_f32_e32 v49, v49
	v_add_f32_e32 v50, v50, v152
	v_cndmask_b32_e64 v50, v195, v50, s[96:97]
	v_exp_f32_e32 v50, v50
	v_add_f32_e32 v51, v51, v153
	v_cndmask_b32_e64 v51, v195, v51, s[70:71]
	v_exp_f32_e32 v51, v51
	v_add_f32_e32 v52, v52, v154
	v_cndmask_b32_e64 v52, v195, v52, s[64:65]
	v_exp_f32_e32 v52, v52
	v_add_f32_e32 v53, v53, v155
	v_cndmask_b32_e64 v53, v195, v53, s[66:67]
	v_exp_f32_e32 v53, v53
	v_add_f32_e32 v54, v54, v156
	v_cndmask_b32_e64 v54, v195, v54, s[60:61]
	v_exp_f32_e32 v54, v54
	v_add_f32_e32 v55, v55, v157
	v_cndmask_b32_e64 v55, v195, v55, s[68:69]
	v_exp_f32_e32 v55, v55
	v_add_f32_e32 v56, v56, v158
	v_cndmask_b32_e64 v56, v195, v56, s[52:53]
	v_exp_f32_e32 v56, v56
	v_add_f32_e32 v57, v57, v159
	v_cndmask_b32_e64 v57, v195, v57, s[54:55]
	v_exp_f32_e32 v57, v57
	v_add_f32_e32 v58, v58, v160
	v_cndmask_b32_e64 v58, v195, v58, s[40:41]
	v_exp_f32_e32 v58, v58
	v_add_f32_e32 v59, v59, v161
	v_cndmask_b32_e64 v59, v195, v59, s[42:43]
	v_exp_f32_e32 v59, v59
	v_add_f32_e32 v60, v60, v162
	v_cndmask_b32_e64 v60, v195, v60, s[36:37]
	v_exp_f32_e32 v60, v60
	v_add_f32_e32 v61, v61, v163
	v_cndmask_b32_e64 v61, v195, v61, s[46:47]
	v_exp_f32_e32 v61, v61
	v_add_f32_e32 v62, v62, v164
	v_cndmask_b32_e64 v62, v195, v62, s[86:87]
	v_exp_f32_e32 v62, v62
	v_add_f32_e32 v63, v63, v165
	v_cndmask_b32_e64 v63, v195, v63, s[4:5]
	v_exp_f32_e32 v63, v63
	v_add_f32_e32 v32, v32, v166
	v_cndmask_b32_e64 v32, v195, v32, s[78:79]
	v_exp_f32_e32 v32, v32
	v_add_f32_e32 v33, v33, v167
	v_cndmask_b32_e64 v33, v195, v33, s[92:93]
	v_exp_f32_e32 v33, v33
	v_add_f32_e32 v34, v34, v168
	v_cndmask_b32_e64 v34, v195, v34, s[94:95]
	v_exp_f32_e32 v34, v34
	v_add_f32_e32 v35, v35, v169
	v_cndmask_b32_e64 v35, v195, v35, s[72:73]
	v_exp_f32_e32 v35, v35
	v_add_f32_e32 v149, 0, v48
	v_add_f32_e32 v149, v149, v49
	v_add_f32_e32 v149, v149, v50
	v_add_f32_e32 v149, v149, v51
	v_add_f32_e32 v149, v149, v52
	v_add_f32_e32 v149, v149, v53
	v_add_f32_e32 v149, v149, v54
	v_add_f32_e32 v149, v149, v55
	v_add_f32_e32 v149, v149, v56
	v_add_f32_e32 v149, v149, v57
	v_add_f32_e32 v149, v149, v58
	v_add_f32_e32 v149, v149, v59
	v_add_f32_e32 v149, v149, v60
	v_add_f32_e32 v149, v149, v61
	v_add_f32_e32 v149, v149, v62
	v_add_f32_e32 v149, v149, v63
	v_add_f32_e32 v149, v149, v32
	v_add_f32_e32 v149, v149, v33
	v_add_f32_e32 v149, v149, v34
	v_add_f32_e32 v149, v149, v35
	v_cvt_pk_bf16_f32 v36, v48, v49
	v_cvt_pk_bf16_f32 v37, v50, v51
	v_cvt_pk_bf16_f32 v38, v52, v53
	v_cvt_pk_bf16_f32 v39, v54, v55
	v_cvt_pk_bf16_f32 v40, v56, v57
	v_cvt_pk_bf16_f32 v41, v58, v59
	v_cvt_pk_bf16_f32 v42, v60, v61
	v_cvt_pk_bf16_f32 v43, v62, v63
	v_cvt_pk_bf16_f32 v44, v32, v33
	v_cvt_pk_bf16_f32 v45, v34, v35
	v_mov_b32_e32 v46, 0
	v_mov_b32_e32 v47, 0
	v_mov_b32_e32 v33, v149
	s_branch .Lna_el_done
; DI bool softmax_tile(f32x16& s0, f32x16& s1, float& m, float& l, float& alpha, bf16x8* pf, int lane, bool first, bool check) {
;     ...
;   float sum = 0.f;
; #pragma unroll
;   for (int i = 0; i < 16; ++i) { s0[i] = __builtin_amdgcn_exp2f(s0[i]); sum += s0[i]; }
; #pragma unroll
;   for (int i = 0; i < 16; ++i) { s1[i] = __builtin_amdgcn_exp2f(s1[i]); sum += s1[i]; }
;   l += sum;
;   pf[0] = pack8(s0, 0); pf[1] = pack8(s0, 8); pf[2] = pack8(s1, 0); pf[3] = pack8(s1, 8);
; DI void attn_na_unit(const Params& p, int li, int b, int r, int hp, char* smem) {
;     ...
;     const int drow = rs + kt - r + 7;
;     const float* trow = tab + hs * 465 + drow * 31;
; #pragma unroll
;     for (int i = 0; i < 16; ++i) {
;       const int kc0 = (i & 3) + 8 * (i >> 2) + 4 * hh;
;       const int kc1 = kc0 + 32;
;       const bool v0 = (unsigned)(kc0 - cs) < 16u;
;       const bool v1 = (unsigned)(kc1 - cs) < 16u;
;       const int d0 = v0 ? (kc0 - wq + 15) : 0;
;       const int d1 = v1 ? (kc1 - wq + 15) : 0;
;       const float b0 = trow[d0], b1 = trow[d1];
;       s0[i] = v0 ? s0[i] + b0 : -1e30f;
;       s1[i] = v1 ? s1[i] + b1 : -1e30f;
;     }
.Lna_el_q1:
	v_add_u32_e32 v149, s9, v130
	ds_read_b32 v150, v149 offset:964
	ds_read_b32 v151, v149 offset:968
	ds_read_b32 v152, v149 offset:972
	ds_read_b32 v153, v149 offset:976
	v_add_u32_e32 v149, s9, v129
	ds_read_b32 v154, v149 offset:868
	v_add_u32_e32 v149, s9, v131
	ds_read_b32 v155, v149 offset:868
	v_add_u32_e32 v149, s9, v132
	ds_read_b32 v156, v149 offset:868
	v_add_u32_e32 v149, s9, v133
	ds_read_b32 v157, v149 offset:868
	v_add_u32_e32 v149, s9, v134
	ds_read_b32 v158, v149 offset:868
	v_add_u32_e32 v149, s9, v135
	ds_read_b32 v159, v149 offset:868
	v_add_u32_e32 v149, s9, v136
	ds_read_b32 v160, v149 offset:868
	v_add_u32_e32 v149, s9, v137
	ds_read_b32 v161, v149 offset:868
	v_add_u32_e32 v149, s9, v138
	ds_read_b32 v162, v149 offset:868
	v_add_u32_e32 v149, s9, v139
	ds_read_b32 v163, v149 offset:868
	v_add_u32_e32 v149, s9, v140
	ds_read_b32 v164, v149 offset:868
	v_add_u32_e32 v149, s9, v141
	ds_read_b32 v165, v149 offset:868
	v_add_u32_e32 v149, s9, v142
	ds_read_b32 v166, v149 offset:868
	v_add_u32_e32 v149, s9, v143
	ds_read_b32 v167, v149 offset:868
	v_add_u32_e32 v149, s9, v146
	ds_read_b32 v168, v149 offset:868
	v_add_u32_e32 v149, s9, v147
	ds_read_b32 v169, v149 offset:868
	s_waitcnt lgkmcnt(0)
	s_nop 7
	v_add_f32_e32 v60, v60, v150
	v_cndmask_b32_e64 v60, v195, v60, s[36:37]
	v_exp_f32_e32 v60, v60
	v_add_f32_e32 v61, v61, v151
	v_cndmask_b32_e64 v61, v195, v61, s[46:47]
	v_exp_f32_e32 v61, v61
	v_add_f32_e32 v62, v62, v152
	v_cndmask_b32_e64 v62, v195, v62, s[86:87]
	v_exp_f32_e32 v62, v62
	v_add_f32_e32 v63, v63, v153
	v_cndmask_b32_e64 v63, v195, v63, s[4:5]
	v_exp_f32_e32 v63, v63
	v_add_f32_e32 v32, v32, v154
	v_cndmask_b32_e64 v32, v195, v32, s[78:79]
	v_exp_f32_e32 v32, v32
	v_add_f32_e32 v33, v33, v155
	v_cndmask_b32_e64 v33, v195, v33, s[92:93]
	v_exp_f32_e32 v33, v33
	v_add_f32_e32 v34, v34, v156
	v_cndmask_b32_e64 v34, v195, v34, s[94:95]
	v_exp_f32_e32 v34, v34
	v_add_f32_e32 v35, v35, v157
	v_cndmask_b32_e64 v35, v195, v35, s[72:73]
	v_exp_f32_e32 v35, v35
	v_add_f32_e32 v36, v36, v158
	v_cndmask_b32_e64 v36, v195, v36, s[80:81]
	v_exp_f32_e32 v36, v36
	v_add_f32_e32 v37, v37, v159
	v_cndmask_b32_e64 v37, v195, v37, s[74:75]
	v_exp_f32_e32 v37, v37
	v_add_f32_e32 v38, v38, v160
	v_cndmask_b32_e64 v38, v195, v38, s[58:59]
	v_exp_f32_e32 v38, v38
	v_add_f32_e32 v39, v39, v161
	v_cndmask_b32_e64 v39, v195, v39, s[48:49]
	v_exp_f32_e32 v39, v39
	v_add_f32_e32 v40, v40, v162
	v_cndmask_b32_e64 v40, v195, v40, s[50:51]
	v_exp_f32_e32 v40, v40
	v_add_f32_e32 v41, v41, v163
	v_cndmask_b32_e64 v41, v195, v41, s[62:63]
	v_exp_f32_e32 v41, v41
	v_add_f32_e32 v42, v42, v164
	v_cndmask_b32_e64 v42, v195, v42, s[38:39]
	v_exp_f32_e32 v42, v42
	v_add_f32_e32 v43, v43, v165
	v_cndmask_b32_e64 v43, v195, v43, s[44:45]
	v_exp_f32_e32 v43, v43
	v_add_f32_e32 v44, v44, v166
	v_cndmask_b32_e64 v44, v195, v44, s[56:57]
	v_exp_f32_e32 v44, v44
	v_add_f32_e32 v45, v45, v167
	v_cndmask_b32_e64 v45, v195, v45, s[82:83]
	v_exp_f32_e32 v45, v45
	v_add_f32_e32 v46, v46, v168
	v_cndmask_b32_e64 v46, v195, v46, s[84:85]
	v_exp_f32_e32 v46, v46
	v_add_f32_e32 v47, v47, v169
	v_cndmask_b32_e64 v47, v195, v47, s[2:3]
	v_exp_f32_e32 v47, v47
	v_add_f32_e32 v149, 0, v60
	v_add_f32_e32 v149, v149, v61
	v_add_f32_e32 v149, v149, v62
	v_add_f32_e32 v149, v149, v63
	v_add_f32_e32 v149, v149, v32
	v_add_f32_e32 v149, v149, v33
	v_add_f32_e32 v149, v149, v34
	v_add_f32_e32 v149, v149, v35
	v_add_f32_e32 v149, v149, v36
	v_add_f32_e32 v149, v149, v37
	v_add_f32_e32 v149, v149, v38
	v_add_f32_e32 v149, v149, v39
	v_add_f32_e32 v149, v149, v40
	v_add_f32_e32 v149, v149, v41
	v_add_f32_e32 v149, v149, v42
	v_add_f32_e32 v149, v149, v43
	v_add_f32_e32 v149, v149, v44
	v_add_f32_e32 v149, v149, v45
	v_add_f32_e32 v149, v149, v46
	v_add_f32_e32 v149, v149, v47
	v_cvt_pk_bf16_f32 v48, v40, v41
	v_cvt_pk_bf16_f32 v49, v42, v43
	v_cvt_pk_bf16_f32 v50, v44, v45
	v_cvt_pk_bf16_f32 v51, v46, v47
	v_cvt_pk_bf16_f32 v44, v32, v33
	v_cvt_pk_bf16_f32 v45, v34, v35
	v_cvt_pk_bf16_f32 v46, v36, v37
	v_cvt_pk_bf16_f32 v47, v38, v39
	v_cvt_pk_bf16_f32 v42, v60, v61
	v_cvt_pk_bf16_f32 v43, v62, v63
	v_mov_b32_e32 v40, 0
	v_mov_b32_e32 v41, 0
	v_mov_b32_e32 v33, v149
.Lna_el_done:
	s_bitcmp1_b32 s100, 6
	s_cbranch_scc1 .Lna_rd_q1
	ds_read_b64_tr_b16 v[52:53], v125 offset:17408
	ds_read_b64_tr_b16 v[54:55], v125 offset:19968
	ds_read_b64_tr_b16 v[56:57], v125 offset:17472
	ds_read_b64_tr_b16 v[58:59], v125 offset:20032

; DI f32x16 mfma32(bf16x8 a, bf16x8 b, f32x16 c) { return __builtin_amdgcn_mfma_f32_32x32x16_bf16(a, b, c, 0, 0, 0); }
; DI bool softmax_tile(f32x16& s0, f32x16& s1, float& m, float& l, float& alpha, bf16x8* pf, int lane, bool first, bool check) {
;     ...
;   if (!check) return false;
;   const float rsum = sum + shx(sum, 32, lane);
;   const bool trig = rsum > 65536.f;
;   const bool resc = (__builtin_amdgcn_ballot_w64(trig) != 0ull);
;   alpha = 1.f;
;   if (resc) {
;     const float d = trig ? (float)(__builtin_amdgcn_frexp_expf(rsum) - 7) : 0.f;
;     alpha = __builtin_amdgcn_exp2f(-d);
;     m += d; l *= alpha;
;   }
;   return resc;
; DI void attn_na_unit(const Params& p, int li, int b, int r, int hp, char* smem) {
;     ...
;     {
;       bf16x8 vf[8];
; #pragma unroll
;       for (int s = 0; s < 4; ++s) { vf[2 * s] = ld_vfrag_tr(vs, vbase, VR, 16 * s, hs * 64); vf[2 * s + 1] = ld_vfrag_tr(vs, vbase, VR, 16 * s, hs * 64 + 32); }
;       __builtin_amdgcn_sched_barrier(0); __builtin_amdgcn_s_setprio(1);
; #pragma unroll
;       for (int s = 0; s < 4; ++s) { O0 = mfma32(vf[2 * s], pf[s], O0); O1 = mfma32(vf[2 * s + 1], pf[s], O1); }
.Lna_rd_q0:
	ds_bpermute_b32 v32, v124, v33
	s_waitcnt lgkmcnt(0)
	v_add_f32_e32 v32, v33, v32
	v_cmp_lt_f32_e32 vcc, s88, v32
	v_frexp_exp_i32_f32_e32 v32, v32
	v_add_u32_e32 v32, -7, v32
	v_cvt_f32_i32_e32 v32, v32
	s_cmp_eq_u64 vcc, 0
	s_cselect_b64 s[6:7], -1, 0
	v_cndmask_b32_e32 v34, 0, v32, vcc
	v_exp_f32_e64 v32, -v34
	s_setprio 1
	s_bitcmp1_b32 s100, 6
	s_cbranch_scc1 .Lna_mm_q1
	v_mfma_f32_32x32x16_bf16 v[16:31], v[52:55], v[36:39], v[16:31]
	v_mfma_f32_32x32x16_bf16 v[0:15], v[56:59], v[36:39], v[0:15]
